# adds: nt hint on the residual epilogues' X stores (Down/out0/out1), on top of the HID-store nt version
# baseline (speedup 1.0000x reference)
.LBB0_363:
	s_lshl_b32 s31, s11, 8
	s_min_i32 s20, s11, 0x100
	s_ashr_i32 s62, s20, 5
	s_add_i32 s63, s31, 0xffff0000
	s_cmpk_gt_i32 s11, 0xff
	s_cselect_b32 s11, s63, s31
	v_add_u32_e32 v146, s11, v1
	s_mul_i32 s62, s62, 0x9000
	s_cselect_b32 s23, s69, s65
	s_cselect_b32 s22, s70, s68
	s_cselect_b32 s21, s37, s49
	s_cselect_b32 s20, s33, s48
	v_lshl_or_b32 v147, s92, 8, v149
	v_lshlrev_b32_e32 v147, 2, v147
	v_lshl_add_u32 v146, v146, 12, v147
	v_add_u32_e32 v147, s62, v147
	v_add_co_u32_e32 v160, vcc, s75, v147
	v_mov_b32_e32 v161, s76
	s_nop 1
	v_addc_co_u32_e32 v161, vcc, 0, v161, vcc
	global_load_dwordx4 v[138:141], v[160:161], off
	global_load_dwordx4 v[142:145], v146, s[22:23]
	s_add_u32 s62, s22, 0x10000
	s_addc_u32 s63, s23, 0
	global_load_dwordx4 v[152:155], v146, s[62:63]
	s_add_u32 s62, s22, 0x20000
	s_addc_u32 s63, s23, 0
	global_load_dwordx4 v[156:159], v146, s[62:63]
	s_add_u32 s62, s22, 0x30000
	s_addc_u32 s63, s23, 0
	global_load_dwordx4 v[164:167], v146, s[62:63]
	s_add_u32 s62, s22, 0x80000
	s_addc_u32 s63, s23, 0
	global_load_dwordx4 v[168:171], v146, s[62:63]
	s_add_u32 s62, s22, 0x90000
	s_addc_u32 s63, s23, 0
	global_load_dwordx4 v[172:175], v146, s[62:63]
	s_add_u32 s62, s22, 0xa0000
	s_addc_u32 s63, s23, 0
	global_load_dwordx4 v[176:179], v146, s[62:63]
	s_add_u32 s62, s22, 0xb0000
	s_addc_u32 s63, s23, 0
	global_load_dwordx4 v[180:183], v146, s[62:63]
	global_load_dwordx4 v[184:187], v146, s[22:23] offset:64
	s_add_u32 s62, s22, 0x10000
	s_addc_u32 s63, s23, 0
	global_load_dwordx4 v[188:191], v146, s[62:63] offset:64
	s_add_u32 s62, s22, 0x20000
	s_addc_u32 s63, s23, 0
	global_load_dwordx4 v[192:195], v146, s[62:63] offset:64
	s_add_u32 s62, s22, 0x30000
	s_addc_u32 s63, s23, 0
	global_load_dwordx4 v[196:199], v146, s[62:63] offset:64
	s_waitcnt vmcnt(12)
	v_pk_mul_f32 v[138:139], v[138:139], 0.5 op_sel_hi:[1,0]
	v_pk_mul_f32 v[140:141], v[140:141], 0.5 op_sel_hi:[1,0]
	s_waitcnt vmcnt(11)
	v_pk_fma_f32 v[142:143], v[126:127], v[138:139], v[142:143]
	v_pk_fma_f32 v[144:145], v[128:129], v[140:141], v[144:145]
	global_store_dwordx4 v146, v[142:145], s[20:21] nt
	s_add_u32 s62, s22, 0x80000
	s_addc_u32 s63, s23, 0
	global_load_dwordx4 v[200:203], v146, s[62:63] offset:64
	s_waitcnt vmcnt(12)
	v_pk_fma_f32 v[152:153], v[122:123], v[138:139], v[152:153]
	v_pk_fma_f32 v[154:155], v[124:125], v[140:141], v[154:155]
	s_add_u32 vcc_lo, s20, 0x10000
	s_addc_u32 vcc_hi, s21, 0
	global_store_dwordx4 v146, v[152:155], vcc nt
	s_add_u32 s62, s22, 0x90000
	s_addc_u32 s63, s23, 0
	global_load_dwordx4 v[126:129], v146, s[62:63] offset:64
	s_waitcnt vmcnt(13)
	v_pk_fma_f32 v[156:157], v[118:119], v[138:139], v[156:157]
	v_pk_fma_f32 v[158:159], v[120:121], v[140:141], v[158:159]
	s_add_u32 vcc_lo, s20, 0x20000
	s_addc_u32 vcc_hi, s21, 0
	global_store_dwordx4 v146, v[156:159], vcc nt
	s_add_u32 s62, s22, 0xa0000
	s_addc_u32 s63, s23, 0
	global_load_dwordx4 v[142:145], v146, s[62:63] offset:64
	s_waitcnt vmcnt(14)
	v_pk_fma_f32 v[164:165], v[114:115], v[138:139], v[164:165]
	v_pk_fma_f32 v[166:167], v[116:117], v[140:141], v[166:167]
	s_add_u32 vcc_lo, s20, 0x30000
	s_addc_u32 vcc_hi, s21, 0
	global_store_dwordx4 v146, v[164:167], vcc nt
	global_load_dwordx4 v[122:125], v[160:161], off offset:64
	s_add_u32 s62, s22, 0xb0000
	s_addc_u32 s63, s23, 0
	global_load_dwordx4 v[152:155], v146, s[62:63] offset:64
	s_waitcnt vmcnt(16)
	v_pk_fma_f32 v[168:169], v[110:111], v[138:139], v[168:169]
	v_pk_fma_f32 v[170:171], v[112:113], v[140:141], v[170:171]
	s_add_u32 vcc_lo, s20, 0x80000
	s_addc_u32 vcc_hi, s21, 0
	global_store_dwordx4 v146, v[168:171], vcc nt
	global_load_dwordx4 v[118:121], v146, s[22:23] offset:512
	s_waitcnt vmcnt(17)
	v_pk_fma_f32 v[172:173], v[106:107], v[138:139], v[172:173]
	v_pk_fma_f32 v[174:175], v[108:109], v[140:141], v[174:175]
	s_add_u32 vcc_lo, s20, 0x90000
	s_addc_u32 vcc_hi, s21, 0
	global_store_dwordx4 v146, v[172:175], vcc nt
	s_add_u32 s62, s22, 0x10000
	s_addc_u32 s63, s23, 0
	global_load_dwordx4 v[156:159], v146, s[62:63] offset:512
	s_waitcnt vmcnt(18)
	v_pk_fma_f32 v[176:177], v[102:103], v[138:139], v[176:177]
	v_pk_fma_f32 v[178:179], v[104:105], v[140:141], v[178:179]
	s_add_u32 vcc_lo, s20, 0xa0000
	s_addc_u32 vcc_hi, s21, 0
	global_store_dwordx4 v146, v[176:179], vcc nt
	s_add_u32 s62, s22, 0x20000
	s_addc_u32 s63, s23, 0
	global_load_dwordx4 v[114:117], v146, s[62:63] offset:512
	s_waitcnt vmcnt(19)
	v_pk_fma_f32 v[180:181], v[98:99], v[138:139], v[180:181]
	v_pk_fma_f32 v[182:183], v[100:101], v[140:141], v[182:183]
	s_add_u32 vcc_lo, s20, 0xb0000
	s_addc_u32 vcc_hi, s21, 0
	global_store_dwordx4 v146, v[180:183], vcc nt
	s_add_u32 s62, s22, 0x30000
	s_addc_u32 s63, s23, 0
	global_load_dwordx4 v[164:167], v146, s[62:63] offset:512
	s_waitcnt vmcnt(9)
	v_pk_mul_f32 v[122:123], v[122:123], 0.5 op_sel_hi:[1,0]
	v_pk_mul_f32 v[124:125], v[124:125], 0.5 op_sel_hi:[1,0]
	s_waitcnt vmcnt(20)
	v_pk_fma_f32 v[184:185], v[94:95], v[122:123], v[184:185]
	v_pk_fma_f32 v[186:187], v[96:97], v[124:125], v[186:187]
	global_store_dwordx4 v146, v[184:187], s[20:21] offset:64 nt
	s_add_u32 s62, s22, 0x80000
	s_addc_u32 s63, s23, 0
	global_load_dwordx4 v[110:113], v146, s[62:63] offset:512
	s_waitcnt vmcnt(21)
	v_pk_fma_f32 v[188:189], v[90:91], v[122:123], v[188:189]
	v_pk_fma_f32 v[190:191], v[92:93], v[124:125], v[190:191]
	s_add_u32 vcc_lo, s20, 0x10000
	s_addc_u32 vcc_hi, s21, 0
	global_store_dwordx4 v146, v[188:191], vcc offset:64 nt
	s_add_u32 s62, s22, 0x90000
	s_addc_u32 s63, s23, 0
	global_load_dwordx4 v[168:171], v146, s[62:63] offset:512
	s_waitcnt vmcnt(22)
	v_pk_fma_f32 v[192:193], v[86:87], v[122:123], v[192:193]
	v_pk_fma_f32 v[194:195], v[88:89], v[124:125], v[194:195]
	s_add_u32 vcc_lo, s20, 0x20000
	s_addc_u32 vcc_hi, s21, 0
	global_store_dwordx4 v146, v[192:195], vcc offset:64 nt
	s_add_u32 s62, s22, 0xa0000
	s_addc_u32 s63, s23, 0
	global_load_dwordx4 v[106:109], v146, s[62:63] offset:512
	s_waitcnt vmcnt(23)
	v_pk_fma_f32 v[196:197], v[82:83], v[122:123], v[196:197]
	v_pk_fma_f32 v[198:199], v[84:85], v[124:125], v[198:199]
	s_add_u32 vcc_lo, s20, 0x30000
	s_addc_u32 vcc_hi, s21, 0
	global_store_dwordx4 v146, v[196:199], vcc offset:64 nt
	global_load_dwordx4 v[172:175], v[160:161], off offset:512
	s_add_u32 s62, s22, 0xb0000
	s_addc_u32 s63, s23, 0
	global_load_dwordx4 v[102:105], v146, s[62:63] offset:512
	s_waitcnt vmcnt(24)
	v_pk_fma_f32 v[200:201], v[78:79], v[122:123], v[200:201]
	v_pk_fma_f32 v[202:203], v[80:81], v[124:125], v[202:203]
	s_add_u32 vcc_lo, s20, 0x80000
	s_addc_u32 vcc_hi, s21, 0
	global_store_dwordx4 v146, v[200:203], vcc offset:64 nt
	global_load_dwordx4 v[176:179], v146, s[22:23] offset:576
	s_waitcnt vmcnt(24)
	v_pk_fma_f32 v[126:127], v[74:75], v[122:123], v[126:127]
	v_pk_fma_f32 v[128:129], v[76:77], v[124:125], v[128:129]
	s_add_u32 vcc_lo, s20, 0x90000
	s_addc_u32 vcc_hi, s21, 0
	global_store_dwordx4 v146, v[126:129], vcc offset:64 nt
	s_add_u32 s62, s22, 0x10000
	s_addc_u32 s63, s23, 0
	global_load_dwordx4 v[98:101], v146, s[62:63] offset:576
	s_waitcnt vmcnt(24)
	v_pk_fma_f32 v[142:143], v[70:71], v[122:123], v[142:143]
	v_pk_fma_f32 v[144:145], v[72:73], v[124:125], v[144:145]
	s_add_u32 vcc_lo, s20, 0xa0000
	s_addc_u32 vcc_hi, s21, 0
	global_store_dwordx4 v146, v[142:145], vcc offset:64 nt
	s_add_u32 s62, s22, 0x20000
	s_addc_u32 s63, s23, 0
	global_load_dwordx4 v[180:183], v146, s[62:63] offset:576
	s_waitcnt vmcnt(23)
	v_pk_fma_f32 v[152:153], v[66:67], v[122:123], v[152:153]
	v_pk_fma_f32 v[154:155], v[68:69], v[124:125], v[154:155]
	s_add_u32 vcc_lo, s20, 0xb0000
	s_addc_u32 vcc_hi, s21, 0
	global_store_dwordx4 v146, v[152:155], vcc offset:64 nt
	s_add_u32 s62, s22, 0x30000
	s_addc_u32 s63, s23, 0
	global_load_dwordx4 v[138:141], v146, s[62:63] offset:576
	s_waitcnt vmcnt(9)
	v_pk_mul_f32 v[172:173], v[172:173], 0.5 op_sel_hi:[1,0]
	v_pk_mul_f32 v[174:175], v[174:175], 0.5 op_sel_hi:[1,0]
	s_waitcnt vmcnt(23)
	v_pk_fma_f32 v[118:119], v[62:63], v[172:173], v[118:119]
	v_pk_fma_f32 v[120:121], v[64:65], v[174:175], v[120:121]
	global_store_dwordx4 v146, v[118:121], s[20:21] offset:512 nt
	s_add_u32 s62, s22, 0x80000
	s_addc_u32 s63, s23, 0
	global_load_dwordx4 v[94:97], v146, s[62:63] offset:576
	s_waitcnt vmcnt(23)
	v_pk_fma_f32 v[156:157], v[58:59], v[172:173], v[156:157]
	v_pk_fma_f32 v[158:159], v[60:61], v[174:175], v[158:159]
	s_add_u32 vcc_lo, s20, 0x10000
	s_addc_u32 vcc_hi, s21, 0
	global_store_dwordx4 v146, v[156:159], vcc offset:512 nt
	s_add_u32 s62, s22, 0x90000
	s_addc_u32 s63, s23, 0
	global_load_dwordx4 v[184:187], v146, s[62:63] offset:576
	s_waitcnt vmcnt(23)
	v_pk_fma_f32 v[114:115], v[54:55], v[172:173], v[114:115]
	v_pk_fma_f32 v[116:117], v[56:57], v[174:175], v[116:117]
	s_add_u32 vcc_lo, s20, 0x20000
	s_addc_u32 vcc_hi, s21, 0
	global_store_dwordx4 v146, v[114:117], vcc offset:512 nt
	s_add_u32 s62, s22, 0xa0000
	s_addc_u32 s63, s23, 0
	global_load_dwordx4 v[90:93], v146, s[62:63] offset:576
	s_waitcnt vmcnt(23)
	v_pk_fma_f32 v[164:165], v[50:51], v[172:173], v[164:165]
	v_pk_fma_f32 v[166:167], v[52:53], v[174:175], v[166:167]
	s_add_u32 vcc_lo, s20, 0x30000
	s_addc_u32 vcc_hi, s21, 0
	global_store_dwordx4 v146, v[164:167], vcc offset:512 nt
	global_load_dwordx4 v[188:191], v[160:161], off offset:576
	s_add_u32 s62, s22, 0xb0000
	s_addc_u32 s63, s23, 0
	global_load_dwordx4 v[86:89], v146, s[62:63] offset:576
	s_waitcnt vmcnt(24)
	v_pk_fma_f32 v[110:111], v[46:47], v[172:173], v[110:111]
	v_pk_fma_f32 v[112:113], v[48:49], v[174:175], v[112:113]
	s_add_u32 vcc_lo, s20, 0x80000
	s_addc_u32 vcc_hi, s21, 0
	global_store_dwordx4 v146, v[110:113], vcc offset:512 nt
	s_waitcnt vmcnt(23)
	v_pk_fma_f32 v[168:169], v[42:43], v[172:173], v[168:169]
	v_pk_fma_f32 v[170:171], v[44:45], v[174:175], v[170:171]
	s_add_u32 vcc_lo, s20, 0x90000
	s_addc_u32 vcc_hi, s21, 0
	global_store_dwordx4 v146, v[168:171], vcc offset:512 nt
	s_waitcnt vmcnt(22)
	v_pk_fma_f32 v[106:107], v[38:39], v[172:173], v[106:107]
	v_pk_fma_f32 v[108:109], v[40:41], v[174:175], v[108:109]
	s_add_u32 vcc_lo, s20, 0xa0000
	s_addc_u32 vcc_hi, s21, 0
	global_store_dwordx4 v146, v[106:109], vcc offset:512 nt
	s_waitcnt vmcnt(20)
	v_pk_fma_f32 v[102:103], v[34:35], v[172:173], v[102:103]
	v_pk_fma_f32 v[104:105], v[36:37], v[174:175], v[104:105]
	s_add_u32 vcc_lo, s20, 0xb0000
	s_addc_u32 vcc_hi, s21, 0
	global_store_dwordx4 v146, v[102:105], vcc offset:512 nt
	s_waitcnt vmcnt(5)
	v_pk_mul_f32 v[188:189], v[188:189], 0.5 op_sel_hi:[1,0]
	v_pk_mul_f32 v[190:191], v[190:191], 0.5 op_sel_hi:[1,0]
	s_waitcnt vmcnt(19)
	v_pk_fma_f32 v[176:177], v[30:31], v[188:189], v[176:177]
	v_pk_fma_f32 v[178:179], v[32:33], v[190:191], v[178:179]
	global_store_dwordx4 v146, v[176:179], s[20:21] offset:576 nt
	s_waitcnt vmcnt(18)
	v_pk_fma_f32 v[98:99], v[26:27], v[188:189], v[98:99]
	v_pk_fma_f32 v[100:101], v[28:29], v[190:191], v[100:101]
	s_add_u32 vcc_lo, s20, 0x10000
	s_addc_u32 vcc_hi, s21, 0
	global_store_dwordx4 v146, v[98:101], vcc offset:576 nt
	s_waitcnt vmcnt(17)
	v_pk_fma_f32 v[180:181], v[22:23], v[188:189], v[180:181]
	v_pk_fma_f32 v[182:183], v[24:25], v[190:191], v[182:183]
	s_add_u32 vcc_lo, s20, 0x20000
	s_addc_u32 vcc_hi, s21, 0
	global_store_dwordx4 v146, v[180:183], vcc offset:576 nt
	s_waitcnt vmcnt(16)
	v_pk_fma_f32 v[138:139], v[18:19], v[188:189], v[138:139]
	v_pk_fma_f32 v[140:141], v[20:21], v[190:191], v[140:141]
	s_add_u32 vcc_lo, s20, 0x30000
	s_addc_u32 vcc_hi, s21, 0
	global_store_dwordx4 v146, v[138:141], vcc offset:576 nt
	s_waitcnt vmcnt(15)
	v_pk_fma_f32 v[94:95], v[14:15], v[188:189], v[94:95]
	v_pk_fma_f32 v[96:97], v[16:17], v[190:191], v[96:97]
	s_add_u32 vcc_lo, s20, 0x80000
	s_addc_u32 vcc_hi, s21, 0
	global_store_dwordx4 v146, v[94:97], vcc offset:576 nt
	s_waitcnt vmcnt(14)
	v_pk_fma_f32 v[184:185], v[10:11], v[188:189], v[184:185]
	v_pk_fma_f32 v[186:187], v[12:13], v[190:191], v[186:187]
	s_add_u32 vcc_lo, s20, 0x90000
	s_addc_u32 vcc_hi, s21, 0
	global_store_dwordx4 v146, v[184:187], vcc offset:576 nt
	s_waitcnt vmcnt(13)
	v_pk_fma_f32 v[90:91], v[6:7], v[188:189], v[90:91]
	v_pk_fma_f32 v[92:93], v[8:9], v[190:191], v[92:93]
	s_add_u32 vcc_lo, s20, 0xa0000
	s_addc_u32 vcc_hi, s21, 0
	global_store_dwordx4 v146, v[90:93], vcc offset:576 nt
	s_waitcnt vmcnt(11)
	v_pk_fma_f32 v[86:87], v[2:3], v[188:189], v[86:87]
	v_pk_fma_f32 v[88:89], v[4:5], v[190:191], v[88:89]
	s_add_u32 vcc_lo, s20, 0xb0000
	s_addc_u32 vcc_hi, s21, 0
	global_store_dwordx4 v146, v[86:89], vcc offset:576 nt
	s_mov_b32 s11, 0
	s_mov_b64 s[62:63], 0xb0000
	s_mov_b64 s[20:21], -1
	s_and_b64 vcc, exec, s[0:1]
	s_cbranch_vccnz .LBB0_351
	s_andn2_b64 vcc, exec, s[14:15]
	s_cbranch_vccnz .LBB0_350
	s_barrier
	s_branch .LBB0_350

.LBB0_1015:
	s_lshl_b32 s20, s11, 8
	s_min_i32 s18, s11, 0x100
	s_ashr_i32 s21, s18, 5
	s_add_i32 s31, s20, 0xffff0000
	s_cmpk_gt_i32 s11, 0xff
	s_cselect_b32 s11, s31, s20
	v_add_u32_e32 v154, s11, v1
	v_lshl_or_b32 v155, s10, 8, v147
	s_mul_i32 s21, s21, 0x9000
	s_cselect_b32 s19, s37, s49
	s_cselect_b32 s18, s33, s48
	v_lshlrev_b32_e32 v155, 2, v155
	v_lshl_add_u32 v154, v154, 12, v155
	v_add_u32_e32 v155, s21, v155
	v_readlane_b32 s10, v255, 11
	v_readlane_b32 s20, v255, 13
	s_nop 1
	v_add_co_u32_e32 v156, vcc, s10, v155
	v_mov_b32_e32 v157, s20
	s_nop 1
	v_addc_co_u32_e32 v157, vcc, 0, v157, vcc
	global_load_dwordx4 v[130:133], v[156:157], off
	global_load_dwordx4 v[142:145], v154, s[18:19]
	s_add_u32 s10, s18, 0x10000
	s_addc_u32 s11, s19, 0
	global_load_dwordx4 v[150:153], v154, s[10:11]
	s_add_u32 s10, s18, 0x20000
	s_addc_u32 s11, s19, 0
	global_load_dwordx4 v[158:161], v154, s[10:11]
	s_add_u32 s10, s18, 0x30000
	s_addc_u32 s11, s19, 0
	global_load_dwordx4 v[162:165], v154, s[10:11]
	s_add_u32 s10, s18, 0x80000
	s_addc_u32 s11, s19, 0
	global_load_dwordx4 v[166:169], v154, s[10:11]
	s_add_u32 s10, s18, 0x90000
	s_addc_u32 s11, s19, 0
	global_load_dwordx4 v[170:173], v154, s[10:11]
	s_add_u32 s10, s18, 0xa0000
	s_addc_u32 s11, s19, 0
	global_load_dwordx4 v[174:177], v154, s[10:11]
	s_add_u32 s10, s18, 0xb0000
	s_addc_u32 s11, s19, 0
	global_load_dwordx4 v[178:181], v154, s[10:11]
	global_load_dwordx4 v[182:185], v154, s[18:19] offset:64
	s_add_u32 s10, s18, 0x10000
	s_addc_u32 s11, s19, 0
	global_load_dwordx4 v[186:189], v154, s[10:11] offset:64
	s_add_u32 s10, s18, 0x20000
	s_addc_u32 s11, s19, 0
	global_load_dwordx4 v[190:193], v154, s[10:11] offset:64
	s_add_u32 s10, s18, 0x30000
	s_addc_u32 s11, s19, 0
	global_load_dwordx4 v[194:197], v154, s[10:11] offset:64
	s_waitcnt vmcnt(12)
	s_waitcnt vmcnt(11)
	v_pk_fma_f32 v[142:143], v[126:127], v[130:131], v[142:143]
	v_pk_fma_f32 v[144:145], v[128:129], v[132:133], v[144:145]
	global_store_dwordx4 v154, v[142:145], s[18:19] nt
	s_add_u32 s10, s18, 0x80000
	s_addc_u32 s11, s19, 0
	global_load_dwordx4 v[198:201], v154, s[10:11] offset:64
	s_waitcnt vmcnt(12)
	v_pk_fma_f32 v[150:151], v[122:123], v[130:131], v[150:151]
	v_pk_fma_f32 v[152:153], v[124:125], v[132:133], v[152:153]
	s_add_u32 vcc_lo, s18, 0x10000
	s_addc_u32 vcc_hi, s19, 0
	global_store_dwordx4 v154, v[150:153], vcc nt
	s_add_u32 s10, s18, 0x90000
	s_addc_u32 s11, s19, 0
	global_load_dwordx4 v[126:129], v154, s[10:11] offset:64
	s_waitcnt vmcnt(13)
	v_pk_fma_f32 v[158:159], v[118:119], v[130:131], v[158:159]
	v_pk_fma_f32 v[160:161], v[120:121], v[132:133], v[160:161]
	s_add_u32 vcc_lo, s18, 0x20000
	s_addc_u32 vcc_hi, s19, 0
	global_store_dwordx4 v154, v[158:161], vcc nt
	s_add_u32 s10, s18, 0xa0000
	s_addc_u32 s11, s19, 0
	global_load_dwordx4 v[142:145], v154, s[10:11] offset:64
	s_waitcnt vmcnt(14)
	v_pk_fma_f32 v[162:163], v[114:115], v[130:131], v[162:163]
	v_pk_fma_f32 v[164:165], v[116:117], v[132:133], v[164:165]
	s_add_u32 vcc_lo, s18, 0x30000
	s_addc_u32 vcc_hi, s19, 0
	global_store_dwordx4 v154, v[162:165], vcc nt
	global_load_dwordx4 v[122:125], v[156:157], off offset:64
	s_add_u32 s10, s18, 0xb0000
	s_addc_u32 s11, s19, 0
	global_load_dwordx4 v[150:153], v154, s[10:11] offset:64
	s_waitcnt vmcnt(16)
	v_pk_fma_f32 v[166:167], v[110:111], v[130:131], v[166:167]
	v_pk_fma_f32 v[168:169], v[112:113], v[132:133], v[168:169]
	s_add_u32 vcc_lo, s18, 0x80000
	s_addc_u32 vcc_hi, s19, 0
	global_store_dwordx4 v154, v[166:169], vcc nt
	global_load_dwordx4 v[118:121], v154, s[18:19] offset:512
	s_waitcnt vmcnt(17)
	v_pk_fma_f32 v[170:171], v[106:107], v[130:131], v[170:171]
	v_pk_fma_f32 v[172:173], v[108:109], v[132:133], v[172:173]
	s_add_u32 vcc_lo, s18, 0x90000
	s_addc_u32 vcc_hi, s19, 0
	global_store_dwordx4 v154, v[170:173], vcc nt
	s_add_u32 s10, s18, 0x10000
	s_addc_u32 s11, s19, 0
	global_load_dwordx4 v[158:161], v154, s[10:11] offset:512
	s_waitcnt vmcnt(18)
	v_pk_fma_f32 v[174:175], v[102:103], v[130:131], v[174:175]
	v_pk_fma_f32 v[176:177], v[104:105], v[132:133], v[176:177]
	s_add_u32 vcc_lo, s18, 0xa0000
	s_addc_u32 vcc_hi, s19, 0
	global_store_dwordx4 v154, v[174:177], vcc nt
	s_add_u32 s10, s18, 0x20000
	s_addc_u32 s11, s19, 0
	global_load_dwordx4 v[114:117], v154, s[10:11] offset:512
	s_waitcnt vmcnt(19)
	v_pk_fma_f32 v[178:179], v[98:99], v[130:131], v[178:179]
	v_pk_fma_f32 v[180:181], v[100:101], v[132:133], v[180:181]
	s_add_u32 vcc_lo, s18, 0xb0000
	s_addc_u32 vcc_hi, s19, 0
	global_store_dwordx4 v154, v[178:181], vcc nt
	s_add_u32 s10, s18, 0x30000
	s_addc_u32 s11, s19, 0
	global_load_dwordx4 v[162:165], v154, s[10:11] offset:512
	s_waitcnt vmcnt(9)
	s_waitcnt vmcnt(20)
	v_pk_fma_f32 v[182:183], v[94:95], v[122:123], v[182:183]
	v_pk_fma_f32 v[184:185], v[96:97], v[124:125], v[184:185]
	global_store_dwordx4 v154, v[182:185], s[18:19] offset:64 nt
	s_add_u32 s10, s18, 0x80000
	s_addc_u32 s11, s19, 0
	global_load_dwordx4 v[110:113], v154, s[10:11] offset:512
	s_waitcnt vmcnt(21)
	v_pk_fma_f32 v[186:187], v[90:91], v[122:123], v[186:187]
	v_pk_fma_f32 v[188:189], v[92:93], v[124:125], v[188:189]
	s_add_u32 vcc_lo, s18, 0x10000
	s_addc_u32 vcc_hi, s19, 0
	global_store_dwordx4 v154, v[186:189], vcc offset:64 nt
	s_add_u32 s10, s18, 0x90000
	s_addc_u32 s11, s19, 0
	global_load_dwordx4 v[166:169], v154, s[10:11] offset:512
	s_waitcnt vmcnt(22)
	v_pk_fma_f32 v[190:191], v[86:87], v[122:123], v[190:191]
	v_pk_fma_f32 v[192:193], v[88:89], v[124:125], v[192:193]
	s_add_u32 vcc_lo, s18, 0x20000
	s_addc_u32 vcc_hi, s19, 0
	global_store_dwordx4 v154, v[190:193], vcc offset:64 nt
	s_add_u32 s10, s18, 0xa0000
	s_addc_u32 s11, s19, 0
	global_load_dwordx4 v[106:109], v154, s[10:11] offset:512
	s_waitcnt vmcnt(23)
	v_pk_fma_f32 v[194:195], v[82:83], v[122:123], v[194:195]
	v_pk_fma_f32 v[196:197], v[84:85], v[124:125], v[196:197]
	s_add_u32 vcc_lo, s18, 0x30000
	s_addc_u32 vcc_hi, s19, 0
	global_store_dwordx4 v154, v[194:197], vcc offset:64 nt
	global_load_dwordx4 v[170:173], v[156:157], off offset:512
	s_add_u32 s10, s18, 0xb0000
	s_addc_u32 s11, s19, 0
	global_load_dwordx4 v[102:105], v154, s[10:11] offset:512
	s_waitcnt vmcnt(24)
	v_pk_fma_f32 v[198:199], v[78:79], v[122:123], v[198:199]
	v_pk_fma_f32 v[200:201], v[80:81], v[124:125], v[200:201]
	s_add_u32 vcc_lo, s18, 0x80000
	s_addc_u32 vcc_hi, s19, 0
	global_store_dwordx4 v154, v[198:201], vcc offset:64 nt
	global_load_dwordx4 v[174:177], v154, s[18:19] offset:576
	s_waitcnt vmcnt(24)
	v_pk_fma_f32 v[126:127], v[74:75], v[122:123], v[126:127]
	v_pk_fma_f32 v[128:129], v[76:77], v[124:125], v[128:129]
	s_add_u32 vcc_lo, s18, 0x90000
	s_addc_u32 vcc_hi, s19, 0
	global_store_dwordx4 v154, v[126:129], vcc offset:64 nt
	s_add_u32 s10, s18, 0x10000
	s_addc_u32 s11, s19, 0
	global_load_dwordx4 v[98:101], v154, s[10:11] offset:576
	s_waitcnt vmcnt(24)
	v_pk_fma_f32 v[142:143], v[70:71], v[122:123], v[142:143]
	v_pk_fma_f32 v[144:145], v[72:73], v[124:125], v[144:145]
	s_add_u32 vcc_lo, s18, 0xa0000
	s_addc_u32 vcc_hi, s19, 0
	global_store_dwordx4 v154, v[142:145], vcc offset:64 nt
	s_add_u32 s10, s18, 0x20000
	s_addc_u32 s11, s19, 0
	global_load_dwordx4 v[178:181], v154, s[10:11] offset:576
	s_waitcnt vmcnt(23)
	v_pk_fma_f32 v[150:151], v[66:67], v[122:123], v[150:151]
	v_pk_fma_f32 v[152:153], v[68:69], v[124:125], v[152:153]
	s_add_u32 vcc_lo, s18, 0xb0000
	s_addc_u32 vcc_hi, s19, 0
	global_store_dwordx4 v154, v[150:153], vcc offset:64 nt
	s_add_u32 s10, s18, 0x30000
	s_addc_u32 s11, s19, 0
	global_load_dwordx4 v[130:133], v154, s[10:11] offset:576
	s_waitcnt vmcnt(9)
	s_waitcnt vmcnt(23)
	v_pk_fma_f32 v[118:119], v[62:63], v[170:171], v[118:119]
	v_pk_fma_f32 v[120:121], v[64:65], v[172:173], v[120:121]
	global_store_dwordx4 v154, v[118:121], s[18:19] offset:512 nt
	s_add_u32 s10, s18, 0x80000
	s_addc_u32 s11, s19, 0
	global_load_dwordx4 v[94:97], v154, s[10:11] offset:576
	s_waitcnt vmcnt(23)
	v_pk_fma_f32 v[158:159], v[58:59], v[170:171], v[158:159]
	v_pk_fma_f32 v[160:161], v[60:61], v[172:173], v[160:161]
	s_add_u32 vcc_lo, s18, 0x10000
	s_addc_u32 vcc_hi, s19, 0
	global_store_dwordx4 v154, v[158:161], vcc offset:512 nt
	s_add_u32 s10, s18, 0x90000
	s_addc_u32 s11, s19, 0
	global_load_dwordx4 v[182:185], v154, s[10:11] offset:576
	s_waitcnt vmcnt(23)
	v_pk_fma_f32 v[114:115], v[54:55], v[170:171], v[114:115]
	v_pk_fma_f32 v[116:117], v[56:57], v[172:173], v[116:117]
	s_add_u32 vcc_lo, s18, 0x20000
	s_addc_u32 vcc_hi, s19, 0
	global_store_dwordx4 v154, v[114:117], vcc offset:512 nt
	s_add_u32 s10, s18, 0xa0000
	s_addc_u32 s11, s19, 0
	global_load_dwordx4 v[90:93], v154, s[10:11] offset:576
	s_waitcnt vmcnt(23)
	v_pk_fma_f32 v[162:163], v[50:51], v[170:171], v[162:163]
	v_pk_fma_f32 v[164:165], v[52:53], v[172:173], v[164:165]
	s_add_u32 vcc_lo, s18, 0x30000
	s_addc_u32 vcc_hi, s19, 0
	global_store_dwordx4 v154, v[162:165], vcc offset:512 nt
	global_load_dwordx4 v[186:189], v[156:157], off offset:576
	s_add_u32 s10, s18, 0xb0000
	s_addc_u32 s11, s19, 0
	global_load_dwordx4 v[86:89], v154, s[10:11] offset:576
	s_waitcnt vmcnt(24)
	v_pk_fma_f32 v[110:111], v[46:47], v[170:171], v[110:111]
	v_pk_fma_f32 v[112:113], v[48:49], v[172:173], v[112:113]
	s_add_u32 vcc_lo, s18, 0x80000
	s_addc_u32 vcc_hi, s19, 0
	global_store_dwordx4 v154, v[110:113], vcc offset:512 nt
	s_waitcnt vmcnt(23)
	v_pk_fma_f32 v[166:167], v[42:43], v[170:171], v[166:167]
	v_pk_fma_f32 v[168:169], v[44:45], v[172:173], v[168:169]
	s_add_u32 vcc_lo, s18, 0x90000
	s_addc_u32 vcc_hi, s19, 0
	global_store_dwordx4 v154, v[166:169], vcc offset:512 nt
	s_waitcnt vmcnt(22)
	v_pk_fma_f32 v[106:107], v[38:39], v[170:171], v[106:107]
	v_pk_fma_f32 v[108:109], v[40:41], v[172:173], v[108:109]
	s_add_u32 vcc_lo, s18, 0xa0000
	s_addc_u32 vcc_hi, s19, 0
	global_store_dwordx4 v154, v[106:109], vcc offset:512 nt
	s_waitcnt vmcnt(20)
	v_pk_fma_f32 v[102:103], v[34:35], v[170:171], v[102:103]
	v_pk_fma_f32 v[104:105], v[36:37], v[172:173], v[104:105]
	s_add_u32 vcc_lo, s18, 0xb0000
	s_addc_u32 vcc_hi, s19, 0
	global_store_dwordx4 v154, v[102:105], vcc offset:512 nt
	s_waitcnt vmcnt(5)
	s_waitcnt vmcnt(19)
	v_pk_fma_f32 v[174:175], v[30:31], v[186:187], v[174:175]
	v_pk_fma_f32 v[176:177], v[32:33], v[188:189], v[176:177]
	global_store_dwordx4 v154, v[174:177], s[18:19] offset:576 nt
	s_waitcnt vmcnt(18)
	v_pk_fma_f32 v[98:99], v[26:27], v[186:187], v[98:99]
	v_pk_fma_f32 v[100:101], v[28:29], v[188:189], v[100:101]
	s_add_u32 vcc_lo, s18, 0x10000
	s_addc_u32 vcc_hi, s19, 0
	global_store_dwordx4 v154, v[98:101], vcc offset:576 nt
	s_waitcnt vmcnt(17)
	v_pk_fma_f32 v[178:179], v[22:23], v[186:187], v[178:179]
	v_pk_fma_f32 v[180:181], v[24:25], v[188:189], v[180:181]
	s_add_u32 vcc_lo, s18, 0x20000
	s_addc_u32 vcc_hi, s19, 0
	global_store_dwordx4 v154, v[178:181], vcc offset:576 nt
	s_waitcnt vmcnt(16)
	v_pk_fma_f32 v[130:131], v[18:19], v[186:187], v[130:131]
	v_pk_fma_f32 v[132:133], v[20:21], v[188:189], v[132:133]
	s_add_u32 vcc_lo, s18, 0x30000
	s_addc_u32 vcc_hi, s19, 0
	global_store_dwordx4 v154, v[130:133], vcc offset:576 nt
	s_waitcnt vmcnt(15)
	v_pk_fma_f32 v[94:95], v[14:15], v[186:187], v[94:95]
	v_pk_fma_f32 v[96:97], v[16:17], v[188:189], v[96:97]
	s_add_u32 vcc_lo, s18, 0x80000
	s_addc_u32 vcc_hi, s19, 0
	global_store_dwordx4 v154, v[94:97], vcc offset:576 nt
	s_waitcnt vmcnt(14)
	v_pk_fma_f32 v[182:183], v[10:11], v[186:187], v[182:183]
	v_pk_fma_f32 v[184:185], v[12:13], v[188:189], v[184:185]
	s_add_u32 vcc_lo, s18, 0x90000
	s_addc_u32 vcc_hi, s19, 0
	global_store_dwordx4 v154, v[182:185], vcc offset:576 nt
	s_waitcnt vmcnt(13)
	v_pk_fma_f32 v[90:91], v[6:7], v[186:187], v[90:91]
	v_pk_fma_f32 v[92:93], v[8:9], v[188:189], v[92:93]
	s_add_u32 vcc_lo, s18, 0xa0000
	s_addc_u32 vcc_hi, s19, 0
	global_store_dwordx4 v154, v[90:93], vcc offset:576 nt
	s_waitcnt vmcnt(11)
	v_pk_fma_f32 v[86:87], v[2:3], v[186:187], v[86:87]
	v_pk_fma_f32 v[88:89], v[4:5], v[188:189], v[88:89]
	s_add_u32 vcc_lo, s18, 0xb0000
	s_addc_u32 vcc_hi, s19, 0
	global_store_dwordx4 v154, v[86:89], vcc offset:576 nt
	s_mov_b64 s[10:11], 0xb0000
	s_mov_b64 s[18:19], -1
	s_and_b64 vcc, exec, s[0:1]
	s_cbranch_vccnz .LBB0_1003
	s_andn2_b64 vcc, exec, s[8:9]
	s_cbranch_vccnz .LBB0_1002
	s_barrier
	s_branch .LBB0_1002
